# out-proj epilogue: xor-16/xor-32 row-sum exchanges via v_permlane16/32_swap instead of ds_bpermute
# baseline (speedup 1.0000x reference)
; __device__ __forceinline__ u32x4 pack8(const f32x4 v0, const f32x4 v1) { u32x4 w; w.x = cvt_pk_bf16(v0[0], v0[1]); w.y = cvt_pk_bf16(v0[2], v0[3]); w.z = cvt_pk_bf16(v1[0], v1[1]); w.w = cvt_pk_bf16(v1[2], v1[3]); return w; }
;     __device__ __forceinline__ void operator()(const f32x4 (&acc)[2][2][4][2], const Unit& u, int wr, int wc, int fr, int fq) const {
;     ...
;             for (int m = 0; m < 4; ++m) { const int row = row0 + ai * HALF + m * 16; const size_t off = (size_t)row * ldc + col0; float ss = 0.f;
; #pragma unroll
;                 for (int bj = 0; bj < 2; ++bj) { const u32x4 w = *(const u32x4*)(hb + off + bj * HALF);
;                     const f32x4 x0 = {__builtin_bit_cast(float, w.x << 16), __builtin_bit_cast(float, w.x & 0xffff0000u), __builtin_bit_cast(float, w.y << 16), __builtin_bit_cast(float, w.y & 0xffff0000u)};
;                     const f32x4 x1 = {__builtin_bit_cast(float, w.z << 16), __builtin_bit_cast(float, w.z & 0xffff0000u), __builtin_bit_cast(float, w.w << 16), __builtin_bit_cast(float, w.w & 0xffff0000u)};
;                     const f32x4 h0 = x0 + acc[ai][bj][m][0], h1 = x1 + acc[ai][bj][m][1];
;                     ss += ((h0[0] * h0[0] + h0[1] * h0[1]) + (h0[2] * h0[2] + h0[3] * h0[3])) + ((h1[0] * h1[0] + h1[1] * h1[1]) + (h1[2] * h1[2] + h1[3] * h1[3]));
;                     *(u32x4*)(hb + off + bj * HALF) = pack8(h0, h1); }
;                 ss += __shfl_xor(ss, 16); ss += __shfl_xor(ss, 32);
;                 if (fq == 0) red[(ai * HALF + wr * 64 + m * 16 + fr) * 4 + wc] = ss; }
.LBB0_520:
	s_lshl_b32 s13, s48, 8
	v_add_u32_e32 v148, s13, v151
	v_ashrrev_i32_e32 v149, 31, v148
	v_lshl_or_b32 v146, s12, 8, v153
	v_lshlrev_b64 v[160:161], 12, v[148:149]
	v_ashrrev_i32_e32 v147, 31, v146
	v_lshl_add_u64 v[160:161], s[18:19], 0, v[160:161]
	v_lshl_add_u64 v[164:165], v[146:147], 1, v[160:161]
	flat_load_dwordx4 v[160:163], v[164:165]
	v_xor_b32_e32 v159, 32, v158
	s_waitcnt vmcnt(0) lgkmcnt(0)
	v_lshlrev_b32_e32 v166, 16, v160
	v_and_b32_e32 v167, 0xffff0000, v160
	v_lshlrev_b32_e32 v160, 16, v161
	v_and_b32_e32 v161, 0xffff0000, v161
	v_lshlrev_b32_e32 v168, 16, v162
	v_and_b32_e32 v169, 0xffff0000, v162
	v_lshlrev_b32_e32 v162, 16, v163
	v_and_b32_e32 v163, 0xffff0000, v163
	v_pk_add_f32 v[128:129], v[128:129], v[160:161]
	v_pk_add_f32 v[166:167], v[126:127], v[166:167]
	v_pk_add_f32 v[170:171], v[124:125], v[162:163]
	v_pk_add_f32 v[168:169], v[122:123], v[168:169]
	v_cvt_pk_bf16_f32 v124, v166, v167
	v_cvt_pk_bf16_f32 v125, v128, v129
	v_mul_f32_e32 v167, v167, v167
	v_cvt_pk_bf16_f32 v126, v168, v169
	v_cvt_pk_bf16_f32 v127, v170, v171
	flat_load_dwordx4 v[160:163], v[164:165] offset:256
	v_mul_f32_e32 v129, v129, v129
	v_mul_f32_e32 v169, v169, v169
	v_mul_f32_e32 v171, v171, v171
	v_fmac_f32_e32 v167, v166, v166
	v_fmac_f32_e32 v129, v128, v128
	v_fmac_f32_e32 v169, v168, v168
	v_fmac_f32_e32 v171, v170, v170
	v_add_f32_e32 v128, v167, v129
	v_add_f32_e32 v129, v169, v171
	v_add_f32_e32 v168, v128, v129
	v_and_b32_e32 v123, 64, v158
	v_xor_b32_e32 v122, 16, v158
	v_add_u32_e32 v123, 64, v123
	v_cmp_lt_i32_e32 vcc, v122, v123
	flat_store_dwordx4 v[164:165], v[124:127]
	s_waitcnt vmcnt(0) lgkmcnt(0)
	v_lshlrev_b32_e32 v128, 16, v160
	v_and_b32_e32 v129, 0xffff0000, v160
	v_lshlrev_b32_e32 v160, 16, v161
	v_and_b32_e32 v161, 0xffff0000, v161
	v_lshlrev_b32_e32 v166, 16, v162
	v_and_b32_e32 v167, 0xffff0000, v162
	v_lshlrev_b32_e32 v162, 16, v163
	v_and_b32_e32 v163, 0xffff0000, v163
	v_pk_add_f32 v[120:121], v[120:121], v[160:161]
	v_pk_add_f32 v[118:119], v[118:119], v[128:129]
	v_pk_add_f32 v[128:129], v[116:117], v[162:163]
	v_pk_add_f32 v[160:161], v[114:115], v[166:167]
	v_mul_f32_e32 v114, v119, v119
	v_mul_f32_e32 v115, v121, v121
	v_mul_f32_e32 v116, v161, v161
	v_mul_f32_e32 v117, v129, v129
	v_fmac_f32_e32 v114, v118, v118
	v_fmac_f32_e32 v115, v120, v120
	v_fmac_f32_e32 v116, v160, v160
	v_fmac_f32_e32 v117, v128, v128
	v_add_f32_e32 v114, v114, v115
	v_add_f32_e32 v115, v116, v117
	v_cndmask_b32_e32 v122, v158, v122, vcc
	v_add_f32_e32 v114, v114, v115
	v_lshlrev_b32_e32 v122, 2, v122
	v_add_f32_e32 v114, v168, v114
	v_mov_b32_e32 v115, v114
	s_nop 1
	v_permlane16_swap_b32_e32 v115, v114
	v_cmp_lt_i32_e32 vcc, v159, v123
	v_cvt_pk_bf16_f32 v118, v118, v119
	v_cvt_pk_bf16_f32 v119, v120, v121
	v_cvt_pk_bf16_f32 v120, v160, v161
	s_waitcnt lgkmcnt(0)
	v_add_f32_e32 v115, v114, v115
	v_cvt_pk_bf16_f32 v121, v128, v129
	v_cndmask_b32_e32 v116, v158, v159, vcc
	v_lshlrev_b32_e32 v114, 2, v116
	v_mov_b32_e32 v116, v115
	s_nop 1
	v_permlane32_swap_b32_e32 v116, v115
	flat_store_dwordx4 v[164:165], v[118:121] offset:256
	s_and_saveexec_b64 s[48:49], s[2:3]
	s_cbranch_execz .LBB0_522
	s_waitcnt lgkmcnt(0)
	v_add_f32_e32 v115, v115, v116
	ds_write_b32 v154, v115
.LBB0_522:
	s_or_b64 exec, exec, s[48:49]
	s_waitcnt lgkmcnt(0)
	v_or_b32_e32 v116, 16, v148
	v_ashrrev_i32_e32 v117, 31, v116
	v_lshlrev_b64 v[116:117], 12, v[116:117]
	v_lshl_add_u64 v[116:117], s[18:19], 0, v[116:117]
	v_lshl_add_u64 v[120:121], v[146:147], 1, v[116:117]
	flat_load_dwordx4 v[116:119], v[120:121]
	s_waitcnt vmcnt(0) lgkmcnt(0)
	v_lshlrev_b32_e32 v124, 16, v116
	v_and_b32_e32 v125, 0xffff0000, v116
	v_lshlrev_b32_e32 v116, 16, v117
	v_and_b32_e32 v117, 0xffff0000, v117
	v_lshlrev_b32_e32 v126, 16, v118
	v_and_b32_e32 v127, 0xffff0000, v118
	v_lshlrev_b32_e32 v118, 16, v119
	v_and_b32_e32 v119, 0xffff0000, v119
	v_pk_add_f32 v[116:117], v[112:113], v[116:117]
	v_pk_add_f32 v[124:125], v[110:111], v[124:125]
	v_pk_add_f32 v[118:119], v[108:109], v[118:119]
	v_pk_add_f32 v[126:127], v[106:107], v[126:127]
	v_cvt_pk_bf16_f32 v106, v124, v125
	v_cvt_pk_bf16_f32 v107, v116, v117
	v_mul_f32_e32 v115, v125, v125
	v_cvt_pk_bf16_f32 v108, v126, v127
	v_cvt_pk_bf16_f32 v109, v118, v119
	flat_load_dwordx4 v[110:113], v[120:121] offset:256
	v_mul_f32_e32 v117, v117, v117
	v_mul_f32_e32 v123, v127, v127
	v_mul_f32_e32 v119, v119, v119
	v_fmac_f32_e32 v115, v124, v124
	v_fmac_f32_e32 v117, v116, v116
	v_fmac_f32_e32 v123, v126, v126
	v_fmac_f32_e32 v119, v118, v118
	v_add_f32_e32 v115, v115, v117
	v_add_f32_e32 v116, v123, v119
	v_add_f32_e32 v115, v115, v116
	flat_store_dwordx4 v[120:121], v[106:109]
	s_waitcnt vmcnt(0) lgkmcnt(0)
	v_lshlrev_b32_e32 v116, 16, v110
	v_and_b32_e32 v117, 0xffff0000, v110
	v_lshlrev_b32_e32 v110, 16, v111
	v_and_b32_e32 v111, 0xffff0000, v111
	v_lshlrev_b32_e32 v118, 16, v112
	v_and_b32_e32 v119, 0xffff0000, v112
	v_lshlrev_b32_e32 v112, 16, v113
	v_and_b32_e32 v113, 0xffff0000, v113
	v_pk_add_f32 v[104:105], v[104:105], v[110:111]
	v_pk_add_f32 v[102:103], v[102:103], v[116:117]
	v_pk_add_f32 v[110:111], v[100:101], v[112:113]
	v_pk_add_f32 v[112:113], v[98:99], v[118:119]
	v_mul_f32_e32 v98, v103, v103
	v_mul_f32_e32 v99, v105, v105
	v_mul_f32_e32 v100, v113, v113
	v_mul_f32_e32 v101, v111, v111
	v_fmac_f32_e32 v98, v102, v102
	v_fmac_f32_e32 v99, v104, v104
	v_fmac_f32_e32 v100, v112, v112
	v_fmac_f32_e32 v101, v110, v110
	v_add_f32_e32 v98, v98, v99
	v_add_f32_e32 v99, v100, v101
	v_add_f32_e32 v98, v98, v99
	v_add_f32_e32 v98, v115, v98
	v_mov_b32_e32 v99, v98
	s_nop 1
	v_permlane16_swap_b32_e32 v99, v98
	v_cvt_pk_bf16_f32 v100, v102, v103
	v_cvt_pk_bf16_f32 v101, v104, v105
	v_cvt_pk_bf16_f32 v102, v112, v113
	v_cvt_pk_bf16_f32 v103, v110, v111
	s_waitcnt lgkmcnt(0)
	v_add_f32_e32 v98, v98, v99
	v_mov_b32_e32 v99, v98
	s_nop 1
	v_permlane32_swap_b32_e32 v99, v98
	flat_store_dwordx4 v[120:121], v[100:103] offset:256
	s_and_saveexec_b64 s[48:49], s[2:3]
	s_cbranch_execz .LBB0_524
	s_waitcnt lgkmcnt(0)
	v_add_f32_e32 v98, v98, v99
	ds_write_b32 v154, v98 offset:256
; __device__ __forceinline__ u32x4 pack8(const f32x4 v0, const f32x4 v1) { u32x4 w; w.x = cvt_pk_bf16(v0[0], v0[1]); w.y = cvt_pk_bf16(v0[2], v0[3]); w.z = cvt_pk_bf16(v1[0], v1[1]); w.w = cvt_pk_bf16(v1[2], v1[3]); return w; }
;     __device__ __forceinline__ void operator()(const f32x4 (&acc)[2][2][4][2], const Unit& u, int wr, int wc, int fr, int fq) const {
;     ...
;             for (int m = 0; m < 4; ++m) { const int row = row0 + ai * HALF + m * 16; const size_t off = (size_t)row * ldc + col0; float ss = 0.f;
; #pragma unroll
;                 for (int bj = 0; bj < 2; ++bj) { const u32x4 w = *(const u32x4*)(hb + off + bj * HALF);
;                     const f32x4 x0 = {__builtin_bit_cast(float, w.x << 16), __builtin_bit_cast(float, w.x & 0xffff0000u), __builtin_bit_cast(float, w.y << 16), __builtin_bit_cast(float, w.y & 0xffff0000u)};
;                     const f32x4 x1 = {__builtin_bit_cast(float, w.z << 16), __builtin_bit_cast(float, w.z & 0xffff0000u), __builtin_bit_cast(float, w.w << 16), __builtin_bit_cast(float, w.w & 0xffff0000u)};
;                     const f32x4 h0 = x0 + acc[ai][bj][m][0], h1 = x1 + acc[ai][bj][m][1];
;                     ss += ((h0[0] * h0[0] + h0[1] * h0[1]) + (h0[2] * h0[2] + h0[3] * h0[3])) + ((h1[0] * h1[0] + h1[1] * h1[1]) + (h1[2] * h1[2] + h1[3] * h1[3]));
;                     *(u32x4*)(hb + off + bj * HALF) = pack8(h0, h1); }
;                 ss += __shfl_xor(ss, 16); ss += __shfl_xor(ss, 32);
;                 if (fq == 0) red[(ai * HALF + wr * 64 + m * 16 + fr) * 4 + wc] = ss; }
.LBB0_524:
	s_or_b64 exec, exec, s[48:49]
	v_or_b32_e32 v98, 32, v148
	s_waitcnt lgkmcnt(0)
	v_ashrrev_i32_e32 v99, 31, v98
	v_lshlrev_b64 v[98:99], 12, v[98:99]
	v_lshl_add_u64 v[98:99], s[18:19], 0, v[98:99]
	v_lshl_add_u64 v[102:103], v[146:147], 1, v[98:99]
	flat_load_dwordx4 v[98:101], v[102:103]
	s_waitcnt vmcnt(0) lgkmcnt(0)
	v_lshlrev_b32_e32 v104, 16, v98
	v_and_b32_e32 v105, 0xffff0000, v98
	v_lshlrev_b32_e32 v98, 16, v99
	v_and_b32_e32 v99, 0xffff0000, v99
	v_lshlrev_b32_e32 v106, 16, v100
	v_and_b32_e32 v107, 0xffff0000, v100
	v_lshlrev_b32_e32 v100, 16, v101
	v_and_b32_e32 v101, 0xffff0000, v101
	v_pk_add_f32 v[98:99], v[96:97], v[98:99]
	v_pk_add_f32 v[104:105], v[94:95], v[104:105]
	v_pk_add_f32 v[100:101], v[92:93], v[100:101]
	v_pk_add_f32 v[106:107], v[90:91], v[106:107]
	v_cvt_pk_bf16_f32 v90, v104, v105
	v_cvt_pk_bf16_f32 v91, v98, v99
	v_mul_f32_e32 v105, v105, v105
	v_cvt_pk_bf16_f32 v92, v106, v107
	v_cvt_pk_bf16_f32 v93, v100, v101
	flat_load_dwordx4 v[94:97], v[102:103] offset:256
	v_mul_f32_e32 v99, v99, v99
	v_mul_f32_e32 v107, v107, v107
	v_mul_f32_e32 v101, v101, v101
	v_fmac_f32_e32 v105, v104, v104
	v_fmac_f32_e32 v99, v98, v98
	v_fmac_f32_e32 v107, v106, v106
	v_fmac_f32_e32 v101, v100, v100
	v_add_f32_e32 v98, v105, v99
	v_add_f32_e32 v99, v107, v101
	v_add_f32_e32 v104, v98, v99
	flat_store_dwordx4 v[102:103], v[90:93]
	s_waitcnt vmcnt(0) lgkmcnt(0)
	v_lshlrev_b32_e32 v98, 16, v94
	v_and_b32_e32 v99, 0xffff0000, v94
	v_lshlrev_b32_e32 v94, 16, v95
	v_and_b32_e32 v95, 0xffff0000, v95
	v_lshlrev_b32_e32 v100, 16, v96
	v_and_b32_e32 v101, 0xffff0000, v96
	v_lshlrev_b32_e32 v96, 16, v97
	v_and_b32_e32 v97, 0xffff0000, v97
	v_pk_add_f32 v[88:89], v[88:89], v[94:95]
	v_pk_add_f32 v[86:87], v[86:87], v[98:99]
	v_pk_add_f32 v[94:95], v[84:85], v[96:97]
	v_pk_add_f32 v[96:97], v[82:83], v[100:101]
	v_mul_f32_e32 v82, v87, v87
	v_mul_f32_e32 v83, v89, v89
	v_mul_f32_e32 v84, v97, v97
	v_mul_f32_e32 v85, v95, v95
	v_fmac_f32_e32 v82, v86, v86
	v_fmac_f32_e32 v83, v88, v88
	v_fmac_f32_e32 v84, v96, v96
	v_fmac_f32_e32 v85, v94, v94
	v_add_f32_e32 v82, v82, v83
	v_add_f32_e32 v83, v84, v85
	v_add_f32_e32 v82, v82, v83
	v_add_f32_e32 v82, v104, v82
	v_mov_b32_e32 v83, v82
	s_nop 1
	v_permlane16_swap_b32_e32 v83, v82
	v_cvt_pk_bf16_f32 v84, v86, v87
	v_cvt_pk_bf16_f32 v85, v88, v89
	v_cvt_pk_bf16_f32 v86, v96, v97
	v_cvt_pk_bf16_f32 v87, v94, v95
	s_waitcnt lgkmcnt(0)
	v_add_f32_e32 v82, v82, v83
	v_mov_b32_e32 v83, v82
	s_nop 1
	v_permlane32_swap_b32_e32 v83, v82
	flat_store_dwordx4 v[102:103], v[84:87] offset:256
	s_and_saveexec_b64 s[48:49], s[2:3]
	s_cbranch_execz .LBB0_526
	s_waitcnt lgkmcnt(0)
	v_add_f32_e32 v82, v82, v83
	ds_write_b32 v154, v82 offset:512
.LBB0_526:
	s_or_b64 exec, exec, s[48:49]
	v_or_b32_e32 v82, 48, v148
	s_waitcnt lgkmcnt(0)
	v_ashrrev_i32_e32 v83, 31, v82
	v_lshlrev_b64 v[82:83], 12, v[82:83]
	v_lshl_add_u64 v[82:83], s[18:19], 0, v[82:83]
	v_lshl_add_u64 v[86:87], v[146:147], 1, v[82:83]
	flat_load_dwordx4 v[82:85], v[86:87]
	s_waitcnt vmcnt(0) lgkmcnt(0)
	v_lshlrev_b32_e32 v88, 16, v82
	v_and_b32_e32 v89, 0xffff0000, v82
	v_lshlrev_b32_e32 v82, 16, v83
	v_and_b32_e32 v83, 0xffff0000, v83
	v_lshlrev_b32_e32 v90, 16, v84
	v_and_b32_e32 v91, 0xffff0000, v84
	v_lshlrev_b32_e32 v84, 16, v85
	v_and_b32_e32 v85, 0xffff0000, v85
	v_pk_add_f32 v[82:83], v[80:81], v[82:83]
	v_pk_add_f32 v[88:89], v[78:79], v[88:89]
	v_pk_add_f32 v[84:85], v[76:77], v[84:85]
	v_pk_add_f32 v[90:91], v[74:75], v[90:91]
	v_cvt_pk_bf16_f32 v74, v88, v89
	v_cvt_pk_bf16_f32 v75, v82, v83
	v_mul_f32_e32 v89, v89, v89
	v_cvt_pk_bf16_f32 v76, v90, v91
	v_cvt_pk_bf16_f32 v77, v84, v85
	flat_load_dwordx4 v[78:81], v[86:87] offset:256
	v_mul_f32_e32 v83, v83, v83
	v_mul_f32_e32 v91, v91, v91
	v_mul_f32_e32 v85, v85, v85
	v_fmac_f32_e32 v89, v88, v88
	v_fmac_f32_e32 v83, v82, v82
	v_fmac_f32_e32 v91, v90, v90
	v_fmac_f32_e32 v85, v84, v84
	v_add_f32_e32 v82, v89, v83
	v_add_f32_e32 v83, v91, v85
	v_add_f32_e32 v88, v82, v83
	flat_store_dwordx4 v[86:87], v[74:77]
	s_waitcnt vmcnt(0) lgkmcnt(0)
	v_lshlrev_b32_e32 v82, 16, v78
	v_and_b32_e32 v83, 0xffff0000, v78
	v_lshlrev_b32_e32 v78, 16, v79
	v_and_b32_e32 v79, 0xffff0000, v79
	v_lshlrev_b32_e32 v84, 16, v80
	v_and_b32_e32 v85, 0xffff0000, v80
	v_lshlrev_b32_e32 v80, 16, v81
	v_and_b32_e32 v81, 0xffff0000, v81
	v_pk_add_f32 v[72:73], v[72:73], v[78:79]
	v_pk_add_f32 v[70:71], v[70:71], v[82:83]
	v_pk_add_f32 v[78:79], v[68:69], v[80:81]
	v_pk_add_f32 v[80:81], v[66:67], v[84:85]
	v_mul_f32_e32 v66, v71, v71
	v_mul_f32_e32 v67, v73, v73
	v_mul_f32_e32 v68, v81, v81
	v_mul_f32_e32 v69, v79, v79
	v_fmac_f32_e32 v66, v70, v70
	v_fmac_f32_e32 v67, v72, v72
	v_fmac_f32_e32 v68, v80, v80
	v_fmac_f32_e32 v69, v78, v78
	v_add_f32_e32 v66, v66, v67
	v_add_f32_e32 v67, v68, v69
	v_add_f32_e32 v66, v66, v67
	v_add_f32_e32 v66, v88, v66
	v_mov_b32_e32 v67, v66
	s_nop 1
	v_permlane16_swap_b32_e32 v67, v66
	v_cvt_pk_bf16_f32 v68, v70, v71
	v_cvt_pk_bf16_f32 v69, v72, v73
	v_cvt_pk_bf16_f32 v70, v80, v81
	v_cvt_pk_bf16_f32 v71, v78, v79
	s_waitcnt lgkmcnt(0)
	v_add_f32_e32 v66, v66, v67
	v_mov_b32_e32 v67, v66
	s_nop 1
	v_permlane32_swap_b32_e32 v67, v66
	flat_store_dwordx4 v[86:87], v[68:71] offset:256
	s_and_saveexec_b64 s[48:49], s[2:3]
	s_cbranch_execz .LBB0_528
	s_waitcnt lgkmcnt(0)
	v_add_f32_e32 v66, v66, v67
	ds_write_b32 v154, v66 offset:768
; __device__ __forceinline__ u32x4 pack8(const f32x4 v0, const f32x4 v1) { u32x4 w; w.x = cvt_pk_bf16(v0[0], v0[1]); w.y = cvt_pk_bf16(v0[2], v0[3]); w.z = cvt_pk_bf16(v1[0], v1[1]); w.w = cvt_pk_bf16(v1[2], v1[3]); return w; }
;     __device__ __forceinline__ void operator()(const f32x4 (&acc)[2][2][4][2], const Unit& u, int wr, int wc, int fr, int fq) const {
;     ...
;             for (int m = 0; m < 4; ++m) { const int row = row0 + ai * HALF + m * 16; const size_t off = (size_t)row * ldc + col0; float ss = 0.f;
; #pragma unroll
;                 for (int bj = 0; bj < 2; ++bj) { const u32x4 w = *(const u32x4*)(hb + off + bj * HALF);
;                     const f32x4 x0 = {__builtin_bit_cast(float, w.x << 16), __builtin_bit_cast(float, w.x & 0xffff0000u), __builtin_bit_cast(float, w.y << 16), __builtin_bit_cast(float, w.y & 0xffff0000u)};
;                     const f32x4 x1 = {__builtin_bit_cast(float, w.z << 16), __builtin_bit_cast(float, w.z & 0xffff0000u), __builtin_bit_cast(float, w.w << 16), __builtin_bit_cast(float, w.w & 0xffff0000u)};
;                     const f32x4 h0 = x0 + acc[ai][bj][m][0], h1 = x1 + acc[ai][bj][m][1];
;                     ss += ((h0[0] * h0[0] + h0[1] * h0[1]) + (h0[2] * h0[2] + h0[3] * h0[3])) + ((h1[0] * h1[0] + h1[1] * h1[1]) + (h1[2] * h1[2] + h1[3] * h1[3]));
;                     *(u32x4*)(hb + off + bj * HALF) = pack8(h0, h1); }
;                 ss += __shfl_xor(ss, 16); ss += __shfl_xor(ss, 32);
;                 if (fq == 0) red[(ai * HALF + wr * 64 + m * 16 + fr) * 4 + wc] = ss; }
.LBB0_528:
	s_or_b64 exec, exec, s[48:49]
	s_waitcnt lgkmcnt(0)
	v_lshlrev_b64 v[66:67], 12, v[148:149]
	v_lshl_add_u64 v[66:67], s[18:19], 0, v[66:67]
	v_lshl_add_u64 v[66:67], v[146:147], 1, v[66:67]
	v_add_co_u32_e32 v72, vcc, 0x80000, v66
	v_lshl_add_u64 v[74:75], v[66:67], 0, s[14:15]
	s_nop 0
	v_addc_co_u32_e32 v73, vcc, 0, v67, vcc
	flat_load_dwordx4 v[68:71], v[72:73]
	s_waitcnt vmcnt(0) lgkmcnt(0)
	v_lshlrev_b32_e32 v76, 16, v68
	v_and_b32_e32 v77, 0xffff0000, v68
	v_lshlrev_b32_e32 v68, 16, v69
	v_and_b32_e32 v69, 0xffff0000, v69
	v_lshlrev_b32_e32 v78, 16, v70
	v_and_b32_e32 v79, 0xffff0000, v70
	v_lshlrev_b32_e32 v70, 16, v71
	v_and_b32_e32 v71, 0xffff0000, v71
	v_pk_add_f32 v[68:69], v[64:65], v[68:69]
	v_pk_add_f32 v[76:77], v[62:63], v[76:77]
	v_pk_add_f32 v[70:71], v[60:61], v[70:71]
	v_pk_add_f32 v[78:79], v[58:59], v[78:79]
	v_cvt_pk_bf16_f32 v58, v76, v77
	v_cvt_pk_bf16_f32 v59, v68, v69
	v_mul_f32_e32 v77, v77, v77
	v_cvt_pk_bf16_f32 v60, v78, v79
	v_cvt_pk_bf16_f32 v61, v70, v71
	flat_load_dwordx4 v[62:65], v[74:75] offset:256
	v_mul_f32_e32 v69, v69, v69
	v_mul_f32_e32 v79, v79, v79
	v_mul_f32_e32 v71, v71, v71
	v_fmac_f32_e32 v77, v76, v76
	v_fmac_f32_e32 v69, v68, v68
	v_fmac_f32_e32 v79, v78, v78
	v_fmac_f32_e32 v71, v70, v70
	v_add_f32_e32 v68, v77, v69
	v_add_f32_e32 v69, v79, v71
	v_add_f32_e32 v76, v68, v69
	flat_store_dwordx4 v[72:73], v[58:61]
	s_waitcnt vmcnt(0) lgkmcnt(0)
	v_lshlrev_b32_e32 v68, 16, v62
	v_and_b32_e32 v69, 0xffff0000, v62
	v_lshlrev_b32_e32 v62, 16, v63
	v_and_b32_e32 v63, 0xffff0000, v63
	v_lshlrev_b32_e32 v70, 16, v64
	v_and_b32_e32 v71, 0xffff0000, v64
	v_lshlrev_b32_e32 v64, 16, v65
	v_and_b32_e32 v65, 0xffff0000, v65
	v_pk_add_f32 v[56:57], v[56:57], v[62:63]
	v_pk_add_f32 v[54:55], v[54:55], v[68:69]
	v_pk_add_f32 v[62:63], v[52:53], v[64:65]
	v_pk_add_f32 v[64:65], v[50:51], v[70:71]
	v_mul_f32_e32 v50, v55, v55
	v_mul_f32_e32 v51, v57, v57
	v_mul_f32_e32 v52, v65, v65
	v_mul_f32_e32 v53, v63, v63
	v_fmac_f32_e32 v50, v54, v54
	v_fmac_f32_e32 v51, v56, v56
	v_fmac_f32_e32 v52, v64, v64
	v_fmac_f32_e32 v53, v62, v62
	v_add_f32_e32 v50, v50, v51
	v_add_f32_e32 v51, v52, v53
	v_add_f32_e32 v50, v50, v51
	v_add_f32_e32 v50, v76, v50
	v_mov_b32_e32 v51, v50
	s_nop 1
	v_permlane16_swap_b32_e32 v51, v50
	v_cvt_pk_bf16_f32 v52, v54, v55
	v_cvt_pk_bf16_f32 v53, v56, v57
	v_cvt_pk_bf16_f32 v54, v64, v65
	v_cvt_pk_bf16_f32 v55, v62, v63
	s_waitcnt lgkmcnt(0)
	v_add_f32_e32 v50, v50, v51
	v_mov_b32_e32 v51, v50
	s_nop 1
	v_permlane32_swap_b32_e32 v51, v50
	flat_store_dwordx4 v[74:75], v[52:55] offset:256
	s_and_saveexec_b64 s[48:49], s[2:3]
	s_cbranch_execz .LBB0_530
	s_waitcnt lgkmcnt(0)
	v_add_f32_e32 v50, v50, v51
	ds_write_b32 v154, v50 offset:2048
.LBB0_530:
	s_or_b64 exec, exec, s[48:49]
	v_add_co_u32_e32 v54, vcc, 0x90000, v66
	v_lshl_add_u64 v[56:57], v[66:67], 0, s[26:27]
	s_nop 0
	v_addc_co_u32_e32 v55, vcc, 0, v67, vcc
	s_waitcnt lgkmcnt(0)
	flat_load_dwordx4 v[50:53], v[54:55]
	s_waitcnt vmcnt(0) lgkmcnt(0)
	v_lshlrev_b32_e32 v58, 16, v50
	v_and_b32_e32 v59, 0xffff0000, v50
	v_lshlrev_b32_e32 v50, 16, v51
	v_and_b32_e32 v51, 0xffff0000, v51
	v_lshlrev_b32_e32 v60, 16, v52
	v_and_b32_e32 v61, 0xffff0000, v52
	v_lshlrev_b32_e32 v52, 16, v53
	v_and_b32_e32 v53, 0xffff0000, v53
	v_pk_add_f32 v[50:51], v[48:49], v[50:51]
	v_pk_add_f32 v[58:59], v[46:47], v[58:59]
	v_pk_add_f32 v[52:53], v[44:45], v[52:53]
	v_pk_add_f32 v[60:61], v[42:43], v[60:61]
	v_cvt_pk_bf16_f32 v42, v58, v59
	v_cvt_pk_bf16_f32 v43, v50, v51
	v_mul_f32_e32 v59, v59, v59
	v_cvt_pk_bf16_f32 v44, v60, v61
	v_cvt_pk_bf16_f32 v45, v52, v53
	flat_load_dwordx4 v[46:49], v[56:57] offset:256
	v_mul_f32_e32 v51, v51, v51
	v_mul_f32_e32 v61, v61, v61
	v_mul_f32_e32 v53, v53, v53
	v_fmac_f32_e32 v59, v58, v58
	v_fmac_f32_e32 v51, v50, v50
	v_fmac_f32_e32 v61, v60, v60
	v_fmac_f32_e32 v53, v52, v52
	v_add_f32_e32 v50, v59, v51
	v_add_f32_e32 v51, v61, v53
	v_add_f32_e32 v58, v50, v51
	flat_store_dwordx4 v[54:55], v[42:45]
	s_waitcnt vmcnt(0) lgkmcnt(0)
	v_lshlrev_b32_e32 v50, 16, v46
	v_and_b32_e32 v51, 0xffff0000, v46
	v_lshlrev_b32_e32 v46, 16, v47
	v_and_b32_e32 v47, 0xffff0000, v47
	v_lshlrev_b32_e32 v52, 16, v48
	v_and_b32_e32 v53, 0xffff0000, v48
	v_lshlrev_b32_e32 v48, 16, v49
	v_and_b32_e32 v49, 0xffff0000, v49
	v_pk_add_f32 v[40:41], v[40:41], v[46:47]
	v_pk_add_f32 v[38:39], v[38:39], v[50:51]
	v_pk_add_f32 v[46:47], v[36:37], v[48:49]
	v_pk_add_f32 v[48:49], v[34:35], v[52:53]
	v_mul_f32_e32 v34, v39, v39
	v_mul_f32_e32 v35, v41, v41
	v_mul_f32_e32 v36, v49, v49
	v_mul_f32_e32 v37, v47, v47
	v_fmac_f32_e32 v34, v38, v38
	v_fmac_f32_e32 v35, v40, v40
	v_fmac_f32_e32 v36, v48, v48
	v_fmac_f32_e32 v37, v46, v46
	v_add_f32_e32 v34, v34, v35
	v_add_f32_e32 v35, v36, v37
	v_add_f32_e32 v34, v34, v35
	v_add_f32_e32 v34, v58, v34
	v_mov_b32_e32 v35, v34
	s_nop 1
	v_permlane16_swap_b32_e32 v35, v34
	v_cvt_pk_bf16_f32 v36, v38, v39
	v_cvt_pk_bf16_f32 v37, v40, v41
	v_cvt_pk_bf16_f32 v38, v48, v49
	v_cvt_pk_bf16_f32 v39, v46, v47
	s_waitcnt lgkmcnt(0)
	v_add_f32_e32 v34, v34, v35
	v_mov_b32_e32 v35, v34
	s_nop 1
	v_permlane32_swap_b32_e32 v35, v34
	flat_store_dwordx4 v[56:57], v[36:39] offset:256
	s_and_saveexec_b64 s[48:49], s[2:3]
	s_cbranch_execz .LBB0_532
	s_waitcnt lgkmcnt(0)
	v_add_f32_e32 v34, v34, v35
	ds_write_b32 v154, v34 offset:2304
; __device__ __forceinline__ u32x4 pack8(const f32x4 v0, const f32x4 v1) { u32x4 w; w.x = cvt_pk_bf16(v0[0], v0[1]); w.y = cvt_pk_bf16(v0[2], v0[3]); w.z = cvt_pk_bf16(v1[0], v1[1]); w.w = cvt_pk_bf16(v1[2], v1[3]); return w; }
;     __device__ __forceinline__ void operator()(const f32x4 (&acc)[2][2][4][2], const Unit& u, int wr, int wc, int fr, int fq) const {
;     ...
;             for (int m = 0; m < 4; ++m) { const int row = row0 + ai * HALF + m * 16; const size_t off = (size_t)row * ldc + col0; float ss = 0.f;
; #pragma unroll
;                 for (int bj = 0; bj < 2; ++bj) { const u32x4 w = *(const u32x4*)(hb + off + bj * HALF);
;                     const f32x4 x0 = {__builtin_bit_cast(float, w.x << 16), __builtin_bit_cast(float, w.x & 0xffff0000u), __builtin_bit_cast(float, w.y << 16), __builtin_bit_cast(float, w.y & 0xffff0000u)};
;                     const f32x4 x1 = {__builtin_bit_cast(float, w.z << 16), __builtin_bit_cast(float, w.z & 0xffff0000u), __builtin_bit_cast(float, w.w << 16), __builtin_bit_cast(float, w.w & 0xffff0000u)};
;                     const f32x4 h0 = x0 + acc[ai][bj][m][0], h1 = x1 + acc[ai][bj][m][1];
;                     ss += ((h0[0] * h0[0] + h0[1] * h0[1]) + (h0[2] * h0[2] + h0[3] * h0[3])) + ((h1[0] * h1[0] + h1[1] * h1[1]) + (h1[2] * h1[2] + h1[3] * h1[3]));
;                     *(u32x4*)(hb + off + bj * HALF) = pack8(h0, h1); }
;                 ss += __shfl_xor(ss, 16); ss += __shfl_xor(ss, 32);
;                 if (fq == 0) red[(ai * HALF + wr * 64 + m * 16 + fr) * 4 + wc] = ss; }
.LBB0_532:
	s_or_b64 exec, exec, s[48:49]
	s_waitcnt lgkmcnt(0)
	v_lshlrev_b64 v[34:35], 12, v[148:149]
	v_lshl_add_u64 v[34:35], s[18:19], 0, v[34:35]
	v_lshl_add_u64 v[34:35], v[146:147], 1, v[34:35]
	v_add_co_u32_e32 v40, vcc, 0xa0000, v34
	v_lshl_add_u64 v[42:43], v[34:35], 0, s[36:37]
	s_nop 0
	v_addc_co_u32_e32 v41, vcc, 0, v35, vcc
	flat_load_dwordx4 v[36:39], v[40:41]
	s_waitcnt vmcnt(0) lgkmcnt(0)
	v_lshlrev_b32_e32 v44, 16, v36
	v_and_b32_e32 v45, 0xffff0000, v36
	v_lshlrev_b32_e32 v36, 16, v37
	v_and_b32_e32 v37, 0xffff0000, v37
	v_lshlrev_b32_e32 v46, 16, v38
	v_and_b32_e32 v47, 0xffff0000, v38
	v_lshlrev_b32_e32 v38, 16, v39
	v_and_b32_e32 v39, 0xffff0000, v39
	v_pk_add_f32 v[36:37], v[32:33], v[36:37]
	v_pk_add_f32 v[44:45], v[30:31], v[44:45]
	v_pk_add_f32 v[38:39], v[28:29], v[38:39]
	v_pk_add_f32 v[46:47], v[26:27], v[46:47]
	v_cvt_pk_bf16_f32 v26, v44, v45
	v_cvt_pk_bf16_f32 v27, v36, v37
	v_mul_f32_e32 v45, v45, v45
	v_cvt_pk_bf16_f32 v28, v46, v47
	v_cvt_pk_bf16_f32 v29, v38, v39
	flat_load_dwordx4 v[30:33], v[42:43] offset:256
	v_mul_f32_e32 v37, v37, v37
	v_mul_f32_e32 v47, v47, v47
	v_mul_f32_e32 v39, v39, v39
	v_fmac_f32_e32 v45, v44, v44
	v_fmac_f32_e32 v37, v36, v36
	v_fmac_f32_e32 v47, v46, v46
	v_fmac_f32_e32 v39, v38, v38
	v_add_f32_e32 v36, v45, v37
	v_add_f32_e32 v37, v47, v39
	v_add_f32_e32 v44, v36, v37
	flat_store_dwordx4 v[40:41], v[26:29]
	s_waitcnt vmcnt(0) lgkmcnt(0)
	v_lshlrev_b32_e32 v36, 16, v30
	v_and_b32_e32 v37, 0xffff0000, v30
	v_lshlrev_b32_e32 v30, 16, v31
	v_and_b32_e32 v31, 0xffff0000, v31
	v_lshlrev_b32_e32 v38, 16, v32
	v_and_b32_e32 v39, 0xffff0000, v32
	v_lshlrev_b32_e32 v32, 16, v33
	v_and_b32_e32 v33, 0xffff0000, v33
	v_pk_add_f32 v[24:25], v[24:25], v[30:31]
	v_pk_add_f32 v[22:23], v[22:23], v[36:37]
	v_pk_add_f32 v[30:31], v[20:21], v[32:33]
	v_pk_add_f32 v[32:33], v[18:19], v[38:39]
	v_mul_f32_e32 v18, v23, v23
	v_mul_f32_e32 v19, v25, v25
	v_mul_f32_e32 v20, v33, v33
	v_mul_f32_e32 v21, v31, v31
	v_fmac_f32_e32 v18, v22, v22
	v_fmac_f32_e32 v19, v24, v24
	v_fmac_f32_e32 v20, v32, v32
	v_fmac_f32_e32 v21, v30, v30
	v_add_f32_e32 v18, v18, v19
	v_add_f32_e32 v19, v20, v21
	v_add_f32_e32 v18, v18, v19
	v_add_f32_e32 v18, v44, v18
	v_mov_b32_e32 v19, v18
	s_nop 1
	v_permlane16_swap_b32_e32 v19, v18
	v_cvt_pk_bf16_f32 v20, v22, v23
	v_cvt_pk_bf16_f32 v21, v24, v25
	v_cvt_pk_bf16_f32 v22, v32, v33
	v_cvt_pk_bf16_f32 v23, v30, v31
	s_waitcnt lgkmcnt(0)
	v_add_f32_e32 v18, v18, v19
	v_mov_b32_e32 v19, v18
	s_nop 1
	v_permlane32_swap_b32_e32 v19, v18
	flat_store_dwordx4 v[42:43], v[20:23] offset:256
	s_and_saveexec_b64 s[48:49], s[2:3]
	s_cbranch_execz .LBB0_534
	s_waitcnt lgkmcnt(0)
	v_add_f32_e32 v18, v18, v19
	ds_write_b32 v154, v18 offset:2560
.LBB0_534:
	s_or_b64 exec, exec, s[48:49]
	v_add_co_u32_e32 v22, vcc, 0xb0000, v34
	v_lshl_add_u64 v[24:25], v[34:35], 0, s[38:39]
	s_nop 0
	v_addc_co_u32_e32 v23, vcc, 0, v35, vcc
	s_waitcnt lgkmcnt(0)
	flat_load_dwordx4 v[18:21], v[22:23]
	s_waitcnt vmcnt(0) lgkmcnt(0)
	v_lshlrev_b32_e32 v26, 16, v18
	v_and_b32_e32 v27, 0xffff0000, v18
	v_lshlrev_b32_e32 v18, 16, v19
	v_and_b32_e32 v19, 0xffff0000, v19
	v_lshlrev_b32_e32 v28, 16, v20
	v_and_b32_e32 v29, 0xffff0000, v20
	v_lshlrev_b32_e32 v20, 16, v21
	v_and_b32_e32 v21, 0xffff0000, v21
	v_pk_add_f32 v[18:19], v[16:17], v[18:19]
	v_pk_add_f32 v[26:27], v[14:15], v[26:27]
	v_pk_add_f32 v[20:21], v[12:13], v[20:21]
	v_pk_add_f32 v[28:29], v[10:11], v[28:29]
	v_cvt_pk_bf16_f32 v10, v26, v27
	v_cvt_pk_bf16_f32 v11, v18, v19
	v_mul_f32_e32 v27, v27, v27
	v_cvt_pk_bf16_f32 v12, v28, v29
	v_cvt_pk_bf16_f32 v13, v20, v21
	flat_load_dwordx4 v[14:17], v[24:25] offset:256
	v_mul_f32_e32 v19, v19, v19
	v_mul_f32_e32 v29, v29, v29
	v_mul_f32_e32 v21, v21, v21
	v_fmac_f32_e32 v27, v26, v26
	v_fmac_f32_e32 v19, v18, v18
	v_fmac_f32_e32 v29, v28, v28
	v_fmac_f32_e32 v21, v20, v20
	v_add_f32_e32 v18, v27, v19
	v_add_f32_e32 v19, v29, v21
	v_add_f32_e32 v26, v18, v19
	flat_store_dwordx4 v[22:23], v[10:13]
	s_waitcnt vmcnt(0) lgkmcnt(0)
	v_lshlrev_b32_e32 v18, 16, v14
	v_and_b32_e32 v19, 0xffff0000, v14
	v_lshlrev_b32_e32 v14, 16, v15
	v_and_b32_e32 v15, 0xffff0000, v15
	v_lshlrev_b32_e32 v20, 16, v16
	v_and_b32_e32 v21, 0xffff0000, v16
	v_lshlrev_b32_e32 v16, 16, v17
	v_and_b32_e32 v17, 0xffff0000, v17
	v_pk_add_f32 v[8:9], v[8:9], v[14:15]
	v_pk_add_f32 v[6:7], v[6:7], v[18:19]
	v_pk_add_f32 v[14:15], v[4:5], v[16:17]
	v_pk_add_f32 v[16:17], v[2:3], v[20:21]
	v_mul_f32_e32 v2, v7, v7
	v_mul_f32_e32 v3, v9, v9
	v_mul_f32_e32 v4, v17, v17
	v_mul_f32_e32 v5, v15, v15
	v_fmac_f32_e32 v2, v6, v6
	v_fmac_f32_e32 v3, v8, v8
	v_fmac_f32_e32 v4, v16, v16
	v_fmac_f32_e32 v5, v14, v14
	v_add_f32_e32 v2, v2, v3
	v_add_f32_e32 v3, v4, v5
	v_add_f32_e32 v2, v2, v3
	v_add_f32_e32 v2, v26, v2
	v_mov_b32_e32 v3, v2
	s_nop 1
	v_permlane16_swap_b32_e32 v3, v2
	v_cvt_pk_bf16_f32 v4, v6, v7
	v_cvt_pk_bf16_f32 v5, v8, v9
	v_cvt_pk_bf16_f32 v6, v16, v17
	v_cvt_pk_bf16_f32 v7, v14, v15
	s_waitcnt lgkmcnt(0)
	v_add_f32_e32 v2, v2, v3
	v_mov_b32_e32 v3, v2
	s_nop 1
	v_permlane32_swap_b32_e32 v3, v2
	flat_store_dwordx4 v[24:25], v[4:7] offset:256
	s_and_saveexec_b64 s[48:49], s[2:3]
	s_cbranch_execz .LBB0_536
	s_waitcnt lgkmcnt(0)
	v_add_f32_e32 v2, v2, v3
	ds_write_b32 v154, v2 offset:2816
